# hosting guarded by a grid-size check (falls back to the prologue conversion on any other grid)
# baseline (speedup 1.0000x reference)
.LBB0_211:
	s_or_b64 exec, exec, s[6:7]
	v_cvt_f32_u32_e32 v0, s16
	s_sub_i32 s5, 0, s16
	s_add_i32 s4, s16, 0x5fffff
	s_mov_b32 s14, 16
	v_rcp_iflag_f32_e32 v0, v0
	s_nop 0
	v_mul_f32_e32 v0, 0x4f7ffffe, v0
	v_cvt_u32_f32_e32 v0, v0
	s_nop 0
	v_readfirstlane_b32 s6, v0
	s_mul_i32 s5, s5, s6
	s_mul_hi_u32 s5, s6, s5
	s_add_i32 s6, s6, s5
	s_mul_hi_u32 s5, s4, s6
	s_mul_i32 s6, s5, s16
	s_sub_i32 s4, s4, s6
	s_add_i32 s7, s5, 1
	s_sub_i32 s6, s4, s16
	s_cmp_ge_u32 s4, s16
	s_cselect_b32 s5, s7, s5
	s_cselect_b32 s4, s6, s4
	s_add_i32 s6, s5, 1
	s_cmp_ge_u32 s4, s16
	s_cselect_b32 s6, s6, s5
	s_cmp_eq_u32 s3, 0x100
	s_cbranch_scc1 .LBB0_234
	s_cmp_lt_u32 s6, 19
	s_cbranch_scc1 .LBB0_227
	s_mul_i32 s7, s3, 0x2200
	s_mul_i32 s8, s3, 0x600
	s_mul_i32 s9, s3, 0x2400
	s_lshl_b32 s10, s3, 13
	s_mov_b32 s13, 16
	v_mov_b32_e32 v71, 0
	s_movk_i32 s11, 0x78
	s_movk_i32 s12, 0xf8
	v_mov_b32_e32 v69, 0x80
	v_mov_b32_e32 v83, 0x138
	v_mov_b32_e32 v84, 0x130

.LBB0_1443:
	s_cmp_gt_i32 s40, 4
	s_cselect_b64 s[4:5], -1, 0
	s_cmp_lt_i32 s41, 5
	s_cselect_b64 s[6:7], -1, 0
	s_or_b64 s[4:5], s[4:5], s[6:7]
	s_and_b64 vcc, exec, s[4:5]
	s_cbranch_vccnz .LBB0_1517
	s_waitcnt lgkmcnt(0)
	s_mov_b64 s[20:21], s[0:1]
	s_load_dwordx8 s[4:11], s[20:21], 0x50
	s_load_dwordx4 s[12:15], s[20:21], 0x70
	s_load_dwordx4 s[16:19], s[20:21], 0x88
	v_mbcnt_lo_u32_b32 v0, -1, 0
	v_mbcnt_hi_u32_b32 v0, -1, v0
	v_and_b32_e32 v1, 63, v0
	v_lshlrev_b32_e32 v1, 2, v1
	s_waitcnt lgkmcnt(0)
	global_load_dword v2, v1, s[4:5]
	global_load_dword v3, v1, s[6:7]
	global_load_dword v4, v1, s[16:17] offset:256
	global_load_dword v5, v1, s[18:19] offset:256
	global_load_dword v6, v1, s[16:17]
	global_load_dword v7, v1, s[18:19]
	global_load_dword v8, v1, s[8:9]
	global_load_dword v9, v1, s[10:11]
	global_load_dword v10, v1, s[12:13]
	global_load_dword v11, v1, s[14:15]
	v_and_b32_e32 v1, 64, v0
	v_xor_b32_e32 v12, 32, v0
	v_add_u32_e32 v1, 64, v1
	v_xor_b32_e32 v13, 16, v0
	v_cmp_lt_i32_e32 vcc, v12, v1
	v_xor_b32_e32 v14, 8, v0
	v_xor_b32_e32 v15, 4, v0
	v_cndmask_b32_e32 v12, v0, v12, vcc
	v_cmp_lt_i32_e32 vcc, v13, v1
	v_xor_b32_e32 v16, 2, v0
	v_xor_b32_e32 v17, 1, v0
	v_cndmask_b32_e32 v13, v0, v13, vcc
	v_cmp_lt_i32_e32 vcc, v14, v1
	v_lshlrev_b32_e32 v133, 2, v12
	v_lshlrev_b32_e32 v12, 2, v13
	v_cndmask_b32_e32 v14, v0, v14, vcc
	v_cmp_lt_i32_e32 vcc, v15, v1
	v_lshlrev_b32_e32 v13, 2, v14
	s_mov_b32 s5, 0
	v_cndmask_b32_e32 v15, v0, v15, vcc
	v_cmp_lt_i32_e32 vcc, v16, v1
	v_lshlrev_b32_e32 v14, 2, v15
	s_cmpk_gt_i32 s2, 0x1ff
	v_cndmask_b32_e32 v16, v0, v16, vcc
	v_cmp_lt_i32_e32 vcc, v17, v1
	v_lshlrev_b32_e32 v15, 2, v16
	s_waitcnt vmcnt(0)
	v_max_f32_e64 v4, |v4|, |v4|
	v_cndmask_b32_e32 v1, v0, v17, vcc
	v_lshlrev_b32_e32 v16, 2, v1
	v_and_b32_e32 v1, 0x7fffffff, v2
	v_and_b32_e32 v17, 0x7fffffff, v3
	v_max_f32_e64 v6, |v6|, |v6|
	v_max_f32_e64 v5, |v5|, |v5|
	v_max_f32_e64 v7, |v7|, |v7|
	v_mul_f32_e32 v18, v8, v9
	v_mul_f32_e32 v19, v10, v11
	ds_bpermute_b32 v1, v133, v1
	ds_bpermute_b32 v17, v133, v17
	v_max_f32_e32 v4, v6, v4
	v_max_f32_e32 v5, v7, v5
	ds_bpermute_b32 v6, v133, v18
	ds_bpermute_b32 v7, v133, v19
	ds_bpermute_b32 v18, v133, v4
	ds_bpermute_b32 v19, v133, v5
	v_max_f32_e64 v2, |v2|, |v2|
	v_max_f32_e64 v3, |v3|, |v3|
	s_waitcnt lgkmcnt(5)
	v_max_f32_e32 v1, v1, v1
	s_waitcnt lgkmcnt(4)
	v_max_f32_e32 v17, v17, v17
	s_waitcnt lgkmcnt(3)
	v_fmac_f32_e32 v6, v8, v9
	s_waitcnt lgkmcnt(2)
	v_fmac_f32_e32 v7, v10, v11
	v_max_f32_e32 v1, v2, v1
	v_max_f32_e32 v2, v3, v17
	s_waitcnt lgkmcnt(1)
	v_max_f32_e32 v3, v18, v18
	s_waitcnt lgkmcnt(0)
	v_max_f32_e32 v8, v19, v19
	ds_bpermute_b32 v9, v12, v6
	ds_bpermute_b32 v10, v12, v7
	ds_bpermute_b32 v11, v12, v1
	ds_bpermute_b32 v17, v12, v2
	v_max_f32_e32 v3, v4, v3
	v_max_f32_e32 v4, v5, v8
	ds_bpermute_b32 v5, v12, v3
	ds_bpermute_b32 v8, v12, v4
	s_waitcnt lgkmcnt(5)
	v_add_f32_e32 v6, v6, v9
	s_waitcnt lgkmcnt(4)
	v_add_f32_e32 v7, v7, v10
	s_waitcnt lgkmcnt(3)
	v_max_f32_e32 v9, v11, v11
	s_waitcnt lgkmcnt(2)
	v_max_f32_e32 v10, v17, v17
	v_max_f32_e32 v1, v1, v9
	v_max_f32_e32 v2, v2, v10
	s_waitcnt lgkmcnt(1)
	v_max_f32_e32 v5, v5, v5
	s_waitcnt lgkmcnt(0)
	v_max_f32_e32 v8, v8, v8
	ds_bpermute_b32 v9, v13, v1
	ds_bpermute_b32 v10, v13, v2
	v_max_f32_e32 v3, v3, v5
	v_max_f32_e32 v4, v4, v8
	ds_bpermute_b32 v5, v13, v3
	ds_bpermute_b32 v8, v13, v4
	s_waitcnt lgkmcnt(3)
	v_max_f32_e32 v9, v9, v9
	s_waitcnt lgkmcnt(2)
	v_max_f32_e32 v10, v10, v10
	v_max_f32_e32 v1, v1, v9
	v_max_f32_e32 v2, v2, v10
	s_waitcnt lgkmcnt(1)
	v_max_f32_e32 v5, v5, v5
	s_waitcnt lgkmcnt(0)
	v_max_f32_e32 v8, v8, v8
	ds_bpermute_b32 v9, v14, v1
	ds_bpermute_b32 v10, v14, v2
	v_max_f32_e32 v3, v3, v5
	v_max_f32_e32 v5, v4, v8
	ds_bpermute_b32 v4, v14, v3
	s_waitcnt lgkmcnt(2)
	v_max_f32_e32 v9, v9, v9
	s_waitcnt lgkmcnt(1)
	v_max_f32_e32 v10, v10, v10
	v_max_f32_e32 v1, v1, v9
	v_max_f32_e32 v9, v2, v10
	s_waitcnt lgkmcnt(0)
	v_max_f32_e32 v2, v4, v4
	ds_bpermute_b32 v11, v13, v6
	ds_bpermute_b32 v12, v13, v7
	ds_bpermute_b32 v4, v15, v1
	ds_bpermute_b32 v10, v15, v9
	v_max_f32_e32 v13, v3, v2
	ds_bpermute_b32 v3, v15, v13
	ds_bpermute_b32 v8, v14, v5
	s_waitcnt lgkmcnt(3)
	v_max_f32_e32 v2, v4, v4
	s_waitcnt lgkmcnt(2)
	v_max_f32_e32 v4, v10, v10
	v_max_f32_e32 v2, v1, v2
	v_max_f32_e32 v1, v9, v4
	s_waitcnt lgkmcnt(1)
	v_max_f32_e32 v9, v3, v3
	v_add_f32_e32 v6, v6, v11
	v_add_f32_e32 v7, v7, v12
	v_max_f32_e32 v129, v13, v9
	ds_bpermute_b32 v9, v14, v6
	ds_bpermute_b32 v10, v14, v7
	s_waitcnt lgkmcnt(2)
	v_max_f32_e32 v8, v8, v8
	v_max_f32_e32 v5, v5, v8
	ds_bpermute_b32 v8, v15, v5
	s_waitcnt lgkmcnt(2)
	v_add_f32_e32 v6, v6, v9
	s_waitcnt lgkmcnt(1)
	v_add_f32_e32 v7, v7, v10
	ds_bpermute_b32 v9, v15, v6
	ds_bpermute_b32 v10, v15, v7
	s_waitcnt lgkmcnt(2)
	v_max_f32_e32 v8, v8, v8
	v_max_f32_e32 v172, v5, v8
	ds_bpermute_b32 v4, v16, v2
	s_waitcnt lgkmcnt(2)
	v_add_f32_e32 v8, v6, v9
	s_waitcnt lgkmcnt(1)
	v_add_f32_e32 v6, v7, v10
	ds_bpermute_b32 v3, v16, v1
	ds_bpermute_b32 v171, v16, v129
	ds_bpermute_b32 v173, v16, v172
	ds_bpermute_b32 v9, v16, v8
	ds_bpermute_b32 v7, v16, v6
	v_add_u32_e32 v5, s63, v0
	s_nop 0
	v_readfirstlane_b32 s3, v5
	s_cbranch_scc1 .LBB0_1467
	s_waitcnt lgkmcnt(1)
	v_add_f32_e32 v8, v8, v9
	s_mov_b32 s4, 0x3fb8aa3b
	v_mul_f32_e32 v9, 0x3fb8aa3b, v8
	v_fma_f32 v10, v8, s4, -v9
	v_rndne_f32_e32 v11, v9
	v_fmac_f32_e32 v10, 0x32a5705f, v8
	v_sub_f32_e32 v9, v9, v11
	v_add_f32_e32 v9, v9, v10
	v_exp_f32_e32 v9, v9
	v_cvt_i32_f32_e32 v10, v11
	s_waitcnt lgkmcnt(0)
	v_add_f32_e32 v6, v6, v7
	v_mul_f32_e32 v7, 0x3fb8aa3b, v6
	v_rndne_f32_e32 v11, v7
	v_ldexp_f32 v9, v9, v10
	v_fma_f32 v10, v6, s4, -v7
	v_fmac_f32_e32 v10, 0x32a5705f, v6
	v_sub_f32_e32 v7, v7, v11
	v_add_f32_e32 v7, v7, v10
	v_exp_f32_e32 v7, v7
	v_cvt_i32_f32_e32 v10, v11
	s_mov_b32 s6, 0xc2ce8ed0
	v_cmp_ngt_f32_e32 vcc, s6, v8
	s_mov_b32 s7, 0x42b17218
	v_mov_b32_e32 v11, 0x7f800000
	v_cndmask_b32_e32 v9, 0, v9, vcc
	v_cmp_nlt_f32_e32 vcc, s7, v8
	v_ldexp_f32 v7, v7, v10
	v_max_f32_e32 v4, v4, v4
	v_cndmask_b32_e32 v8, v11, v9, vcc
	v_cmp_ngt_f32_e32 vcc, s6, v6
	v_max_f32_e32 v2, v2, v2
	v_max_f32_e32 v2, v2, v4
	v_cndmask_b32_e32 v7, 0, v7, vcc
	v_cmp_nlt_f32_e32 vcc, s7, v6
	v_mul_f32_e32 v2, 0x3fb8aa3b, v2
	v_max_f32_e32 v3, v3, v3
	v_cndmask_b32_e32 v6, v11, v7, vcc
	v_max_f32_e32 v1, v1, v1
	v_sub_f32_e32 v6, v8, v6
	v_mul_f32_e32 v2, 0x41000000, v2
	v_max_f32_e32 v1, v1, v3
	v_add_f32_e32 v136, 0x3e4ccccd, v6
	v_and_b32_e32 v6, 0xff, v5
	v_mul_f32_e32 v1, v2, v1
	v_and_b32_e32 v174, 31, v0
	v_bfe_u32 v2, v5, 5, 3
	v_lshrrev_b32_e32 v3, 1, v5
	s_load_dwordx4 s[28:31], s[20:21], 0x1d8
	s_ashr_i32 s3, s3, 8
	v_bfe_u32 v17, v6, 5, 1
	v_and_b32_e32 v175, 0x60, v3
	v_bitop3_b32 v3, v2, v174, 1 bitop3:0x6c
	s_lshl_b32 s4, s3, 12
	v_lshlrev_b32_e32 v128, 4, v6
	v_lshlrev_b32_e32 v177, 4, v3
	v_bitop3_b32 v3, v17, v174, 2 bitop3:0x36
	v_bitop3_b32 v2, v2, v174, 6 bitop3:0x36
	v_or_b32_e32 v138, s4, v128
	v_lshlrev_b32_e32 v178, 4, v3
	v_bitop3_b32 v3, v17, v174, 4 bitop3:0x36
	v_lshlrev_b32_e32 v180, 4, v2
	v_bfe_u32 v2, v0, 3, 2
	v_lshlrev_b32_e32 v179, 4, v3
	v_lshlrev_b32_e32 v3, 11, v17
	v_bitop3_b32 v0, v2, v0, 31 bitop3:0x78
	v_ashrrev_i32_e32 v139, 31, v138
	v_lshl_or_b32 v168, v0, 4, v3
	v_bitop3_b32 v0, v2, v174, 4 bitop3:0x36
	s_waitcnt lgkmcnt(0)
	v_lshl_add_u64 v[140:141], s[28:29], 0, v[138:139]
	s_mov_b64 s[8:9], 0x220c000
	s_lshl_b32 s36, s3, 1
	v_lshl_or_b32 v169, v0, 4, v3
	v_mov_b32_e32 v0, 0xfffffc00
	v_lshl_add_u64 v[142:143], v[140:141], 0, s[8:9]
	s_mov_b64 s[8:9], 0x6000
	v_lshlrev_b32_e32 v16, 3, v17
	v_bitop3_b32 v181, s4, v0, v128 bitop3:0xc8
	v_mul_f32_e32 v0, 0xbf828f5c, v1
	s_add_u32 s6, s0, 0x230
	v_lshl_add_u64 v[144:145], v[140:141], 0, s[8:9]
	s_mov_b64 s[8:9], 0x226000
	v_mov_b32_e32 v131, 0
	v_lshlrev_b32_e32 v176, 10, v17
	v_add_u32_e32 v182, 0, v181
	v_mov_b32_e32 v1, v0
	v_mov_b32_e32 v2, v0
	v_mov_b32_e32 v3, v0
	v_mov_b32_e32 v4, v0
	v_mov_b32_e32 v5, v0
	v_mov_b32_e32 v6, v0
	v_mov_b32_e32 v7, v0
	v_mov_b32_e32 v8, v0
	v_mov_b32_e32 v9, v0
	v_mov_b32_e32 v10, v0
	v_mov_b32_e32 v11, v0
	v_mov_b32_e32 v12, v0
	v_mov_b32_e32 v13, v0
	v_mov_b32_e32 v14, v0
	v_mov_b32_e32 v15, v0
	v_lshlrev_b32_e32 v132, 2, v17
	s_addc_u32 s7, s1, 0
	v_mov_b32_e32 v137, v136
	v_or_b32_e32 v170, v175, v174
	v_lshl_add_u64 v[146:147], v[140:141], 0, s[8:9]
	s_movk_i32 s37, 0x2400
	s_mov_b64 s[8:9], 0x2200000
	s_mov_b64 s[10:11], 0x2000
	s_add_i32 s42, 0, 0x10000
	s_add_i32 s43, 0, 0x14000
	s_add_i32 s44, 0, 0x16000
	s_mov_b64 s[12:13], 0x4000
	v_lshlrev_b32_e32 v134, 1, v16
	v_mov_b32_e32 v183, 0x358637bd
	s_mov_b32 s45, 0x800000
	s_mov_b32 s46, s2
	s_mov_b32 s98, 16
	s_load_dwordx4 s[76:79], s[0:1], 0x130
	s_load_dwordx2 s[80:81], s[0:1], 0x140
	s_load_dwordx4 s[84:87], s[0:1], 0x1c0
	s_load_dword s96, s[0:1], 0x230
	s_waitcnt lgkmcnt(0)
	s_cmp_eq_u32 s96, 0x100
	s_cselect_b32 s97, 64, 0
	s_branch .LBB0_1447

.LBB0_1447:
	s_lshl_b32 s4, s46, 5
	s_and_b32 s14, s46, 0x3fffff00
	s_and_b32 s4, s4, 0xe0
	s_bfe_u32 s15, s46, 0x50003
	s_or_b32 s4, s14, s4
	s_or_b32 s4, s4, s15
	s_lshl_b32 s4, s4, 2
	s_add_i32 s18, s4, s36
	s_lshr_b32 s4, s18, 5
	s_and_b32 s48, s4, 14
	s_ashr_i32 s14, s18, 9
	s_bfe_u32 s16, s18, 0x30006
	s_lshl_b32 s47, s48, 6
	s_ashr_i32 s15, s14, 31
	s_mul_i32 s34, s16, 0x440000
	s_add_u32 s16, s28, s34
	s_addc_u32 s17, s29, 0
	s_lshl_b32 s18, s18, 6
	s_mul_i32 s22, s14, 0x1100
	s_and_b32 s18, s18, 0xf80
	s_mul_hi_i32 s19, s14, 0x1100
	v_or_b32_e32 v130, s18, v170
	s_add_u32 s18, s22, 0x100
	s_addc_u32 s19, s19, 0
	v_lshl_add_u64 v[16:17], s[18:19], 0, v[130:131]
	v_mov_b64_e32 v[18:19], s[30:31]
	v_mad_u64_u32 v[150:151], s[18:19], v16, s37, v[18:19]
	v_mad_i32_i24 v151, v17, s37, v151
	s_lshl_b32 s18, s48, 7
	s_mov_b32 s19, s5
	v_lshl_add_u64 v[16:17], v[150:151], 0, s[18:19]
	v_mov_b32_e32 v135, v131
	s_mul_i32 s22, s14, 0x44
	s_mul_i32 s4, s48, 0x220000
	v_lshl_add_u64 v[16:17], v[16:17], 0, v[134:135]
	s_ashr_i32 s23, s22, 31
	global_load_dwordx4 v[112:115], v[16:17], off
	global_load_dwordx4 v[116:119], v[16:17], off offset:32
	global_load_dwordx4 v[120:123], v[16:17], off offset:64
	global_load_dwordx4 v[124:127], v[16:17], off offset:96
	v_lshl_add_u64 v[16:17], v[140:141], 0, s[4:5]
	v_lshl_add_u64 v[18:19], s[16:17], 0, v[138:139]
	s_lshl_b64 s[16:17], s[22:23], 13
	v_readfirstlane_b32 s4, v182
	v_add_u32_e32 v209, 0x4000, v182
	v_lshl_add_u64 v[18:19], v[18:19], 0, s[8:9]
	v_lshl_add_u64 v[20:21], v[16:17], 0, s[16:17]
	s_lshl_b64 s[24:25], s[22:23], 14
	s_mov_b32 m0, s4
	v_readfirstlane_b32 s4, v209
	v_add_u32_e32 v211, 0x6000, v182
	s_or_b32 s26, s22, 1
	s_barrier
	v_lshl_add_u64 v[152:153], v[18:19], 0, s[24:25]
	global_load_lds_dwordx4 v[20:21], off
	s_mov_b32 m0, s4
	v_readfirstlane_b32 s4, v211
	s_ashr_i32 s27, s26, 31
	v_add_u32_e32 v213, 0x8000, v182
	global_load_lds_dwordx4 v[152:153], off
	v_lshl_add_u64 v[154:155], v[152:153], 0, s[10:11]
	s_mov_b32 m0, s4
	s_lshl_b64 s[18:19], s[26:27], 13
	s_lshl_b64 s[26:27], s[26:27], 14
	v_readfirstlane_b32 s4, v213
	v_add_u32_e32 v215, 0xc000, v182
	global_load_lds_dwordx4 v[154:155], off
	v_lshl_add_u64 v[20:21], v[16:17], 0, s[18:19]
	v_lshl_add_u64 v[156:157], v[18:19], 0, s[26:27]
	s_mov_b32 m0, s4
	v_readfirstlane_b32 s4, v215
	v_add_u32_e32 v217, 0xe000, v182
	s_or_b32 s26, s22, 2
	global_load_lds_dwordx4 v[20:21], off
	s_mov_b32 m0, s4
	v_readfirstlane_b32 s4, v217
	s_ashr_i32 s27, s26, 31
	v_add_u32_e32 v218, s42, v181
	global_load_lds_dwordx4 v[156:157], off
	v_lshl_add_u64 v[158:159], v[156:157], 0, s[10:11]
	s_mov_b32 m0, s4
	s_lshl_b64 s[22:23], s[26:27], 13
	v_readfirstlane_b32 s4, v218
	v_add_u32_e32 v219, s43, v181
	global_load_lds_dwordx4 v[158:159], off
	v_lshl_add_u64 v[16:17], v[16:17], 0, s[22:23]
	s_lshl_b64 s[26:27], s[26:27], 14
	s_mov_b32 m0, s4
	v_readfirstlane_b32 s4, v219
	v_add_u32_e32 v220, s44, v181
	v_lshl_add_u64 v[160:161], v[18:19], 0, s[26:27]
	global_load_lds_dwordx4 v[16:17], off
	s_mov_b32 m0, s4
	v_readfirstlane_b32 s4, v220
	global_load_lds_dwordx4 v[160:161], off
	v_lshl_add_u64 v[162:163], v[160:161], 0, s[10:11]
	s_mov_b32 m0, s4
	s_add_u32 s24, s34, s24
	global_load_lds_dwordx4 v[162:163], off
	s_addc_u32 s25, 0, s25
	s_waitcnt vmcnt(6)
	v_lshl_add_u64 v[148:149], v[142:143], 0, s[24:25]
	s_add_u32 s24, s34, s16
	s_addc_u32 s25, 0, s17
	v_lshl_add_u64 v[164:165], v[144:145], 0, s[24:25]
	s_mov_b32 s4, 0
	s_mov_b32 s49, 0x18000
	v_mov_b64_e32 v[166:167], v[148:149]
	v_mov_b32_e32 v64, v131
	v_mov_b32_e32 v65, v131
	v_mov_b32_e32 v66, v131
	v_mov_b32_e32 v67, v131
	v_mov_b32_e32 v68, v131
	v_mov_b32_e32 v69, v131
	v_mov_b32_e32 v70, v131
	v_mov_b32_e32 v71, v131
	v_mov_b32_e32 v72, v131
	v_mov_b32_e32 v73, v131
	v_mov_b32_e32 v74, v131
	v_mov_b32_e32 v75, v131
	v_mov_b32_e32 v76, v131
	v_mov_b32_e32 v77, v131
	v_mov_b32_e32 v78, v131
	v_mov_b32_e32 v79, v131
	v_mov_b32_e32 v48, v131
	v_mov_b32_e32 v49, v131
	v_mov_b32_e32 v50, v131
	v_mov_b32_e32 v51, v131
	v_mov_b32_e32 v52, v131
	v_mov_b32_e32 v53, v131
	v_mov_b32_e32 v54, v131
	v_mov_b32_e32 v55, v131
	v_mov_b32_e32 v56, v131
	v_mov_b32_e32 v57, v131
	v_mov_b32_e32 v58, v131
	v_mov_b32_e32 v59, v131
	v_mov_b32_e32 v60, v131
	v_mov_b32_e32 v61, v131
	v_mov_b32_e32 v62, v131
	v_mov_b32_e32 v63, v131
	v_mov_b32_e32 v32, v131
	v_mov_b32_e32 v33, v131
	v_mov_b32_e32 v34, v131
	v_mov_b32_e32 v35, v131
	v_mov_b32_e32 v36, v131
	v_mov_b32_e32 v37, v131
	v_mov_b32_e32 v38, v131
	v_mov_b32_e32 v39, v131
	v_mov_b32_e32 v40, v131
	v_mov_b32_e32 v41, v131
	v_mov_b32_e32 v42, v131
	v_mov_b32_e32 v43, v131
	v_mov_b32_e32 v44, v131
	v_mov_b32_e32 v45, v131
	v_mov_b32_e32 v46, v131
	v_mov_b32_e32 v47, v131
	v_mov_b32_e32 v16, v131
	v_mov_b32_e32 v17, v131
	v_mov_b32_e32 v18, v131
	v_mov_b32_e32 v19, v131
	v_mov_b32_e32 v20, v131
	v_mov_b32_e32 v21, v131
	v_mov_b32_e32 v22, v131
	v_mov_b32_e32 v23, v131
	v_mov_b32_e32 v24, v131
	v_mov_b32_e32 v25, v131
	v_mov_b32_e32 v26, v131
	v_mov_b32_e32 v27, v131
	v_mov_b32_e32 v28, v131
	v_mov_b32_e32 v29, v131
	v_mov_b32_e32 v30, v131
	v_mov_b32_e32 v31, v131
	s_barrier
	s_waitcnt vmcnt(0)
	s_mov_b32 s90, 0
	s_mov_b32 s88, 0
	s_mov_b32 s89, 0
	s_lshr_b32 s91, s2, 7
	s_lshl_b32 s92, s98, 1
	s_add_i32 s91, s91, s92
	s_mul_i32 s92, s91, 0xab
	s_lshr_b32 s92, s92, 9
	s_mul_i32 s93, s92, 3
	s_sub_i32 s91, s91, s93
	v_mbcnt_lo_u32_b32 v222, -1, 0
	v_mbcnt_hi_u32_b32 v222, -1, v222
	s_and_b32 s93, s2, 0x7f
	s_lshl_b32 s93, s93, 9
	s_or_b32 s93, s93, s63
	v_or_b32_e32 v222, s93, v222
	s_cmp_eq_u32 s91, 2
	s_cselect_b32 s93, 12, 11
	v_lshrrev_b32_e32 v223, s93, v222
	v_and_b32_e32 v208, 7, v222
	v_lshl_or_b32 v223, v223, 3, v208
	s_cselect_b32 s93, 6, 5
	v_bfe_u32 v208, v222, 6, s93
	v_lshrrev_b32_e32 v222, 1, v222
	v_and_b32_e32 v222, 28, v222
	v_lshl_or_b32 v222, v208, 5, v222
	v_lshlrev_b32_e32 v222, 2, v222
	s_cselect_b32 s93, 16, 15
	v_lshlrev_b32_e32 v223, s93, v223
	v_add_u32_e32 v222, v223, v222
	s_cselect_b32 s94, 1, 0
	s_lshl_b32 s94, 0x1000, s94
	s_lshl_b32 s92, s92, 23
	s_cmp_eq_u32 s91, 0
	s_cselect_b64 s[100:101], s[76:77], s[78:79]
	s_cmp_eq_u32 s91, 2
	s_cselect_b64 s[100:101], s[80:81], s[100:101]
	s_add_u32 s100, s100, s92
	s_addc_u32 s101, s101, 0
	s_mov_b32 s95, 1
	s_cmp_eq_u32 s97, 0
	s_cselect_b32 s95, 0, s95
	s_branch .LBB0_1449
.LBB0_1448:
	s_cmp_lt_u32 s4, s97
	s_cbranch_scc0 .Lcj_cx_0
	s_and_b32 s93, s4, 7
	s_cmp_eq_u32 s93, 5
	s_cbranch_scc1 .Lcj_c5_0
	s_cmp_eq_u32 s93, 7
	s_cbranch_scc1 .Lcj_c7_0

.LBB0_1455:
	ds_bpermute_b32 v80, v133, v135
	s_waitcnt lgkmcnt(0)
	v_add_f32_e32 v80, v135, v80
	v_div_scale_f32 v81, s[26:27], v80, v80, 1.0
	v_rcp_f32_e32 v82, v81
	v_div_scale_f32 v83, vcc, 1.0, v80, 1.0
	s_or_b32 s26, s48, 1
	v_fma_f32 v84, -v81, v82, 1.0
	v_fmac_f32_e32 v82, v84, v82
	v_mul_f32_e32 v84, v83, v82
	v_fma_f32 v85, -v81, v84, v83
	v_fmac_f32_e32 v84, v85, v82
	v_fma_f32 v81, -v81, v84, v83
	v_div_fmas_f32 v81, v81, v82, v84
	v_div_fixup_f32 v80, v81, v80, 1.0
	v_mul_f32_e32 v64, v64, v80
	v_mul_f32_e32 v65, v65, v80
	v_mul_f32_e32 v66, v66, v80
	v_mul_f32_e32 v67, v67, v80
	v_cvt_pk_bf16_f32 v216, v64, v65
	v_cvt_pk_bf16_f32 v214, v66, v67
	v_mul_f32_e32 v64, v68, v80
	v_mul_f32_e32 v65, v69, v80
	v_mul_f32_e32 v66, v70, v80
	v_mul_f32_e32 v67, v71, v80
	v_cvt_pk_bf16_f32 v212, v64, v65
	v_cvt_pk_bf16_f32 v210, v66, v67
	v_mul_f32_e32 v64, v72, v80
	v_mul_f32_e32 v65, v73, v80
	v_mul_f32_e32 v66, v74, v80
	v_mul_f32_e32 v67, v75, v80
	v_mul_f32_e32 v48, v48, v80
	v_mul_f32_e32 v49, v49, v80
	v_mul_f32_e32 v50, v50, v80
	v_mul_f32_e32 v51, v51, v80
	v_cvt_pk_bf16_f32 v207, v64, v65
	v_cvt_pk_bf16_f32 v206, v66, v67
	v_mul_f32_e32 v64, v76, v80
	v_mul_f32_e32 v65, v77, v80
	v_mul_f32_e32 v66, v78, v80
	v_mul_f32_e32 v67, v79, v80
	v_cvt_pk_bf16_f32 v205, v64, v65
	v_cvt_pk_bf16_f32 v204, v66, v67
	v_cvt_pk_bf16_f32 v203, v48, v49
	v_cvt_pk_bf16_f32 v202, v50, v51
	v_mul_f32_e32 v48, v52, v80
	v_mul_f32_e32 v49, v53, v80
	v_mul_f32_e32 v50, v54, v80
	v_mul_f32_e32 v51, v55, v80
	v_cvt_pk_bf16_f32 v201, v48, v49
	v_cvt_pk_bf16_f32 v200, v50, v51
	v_mul_f32_e32 v48, v56, v80
	v_mul_f32_e32 v49, v57, v80
	v_mul_f32_e32 v50, v58, v80
	v_mul_f32_e32 v51, v59, v80
	v_mul_f32_e32 v32, v32, v80
	v_mul_f32_e32 v33, v33, v80
	v_mul_f32_e32 v34, v34, v80
	v_mul_f32_e32 v35, v35, v80
	v_cvt_pk_bf16_f32 v197, v48, v49
	v_cvt_pk_bf16_f32 v196, v50, v51
	v_mul_f32_e32 v48, v60, v80
	v_mul_f32_e32 v49, v61, v80
	v_mul_f32_e32 v50, v62, v80
	v_mul_f32_e32 v51, v63, v80
	v_cvt_pk_bf16_f32 v199, v48, v49
	v_cvt_pk_bf16_f32 v198, v50, v51
	v_cvt_pk_bf16_f32 v193, v32, v33
	v_cvt_pk_bf16_f32 v192, v34, v35
	v_mul_f32_e32 v32, v36, v80
	v_mul_f32_e32 v33, v37, v80
	v_mul_f32_e32 v34, v38, v80
	v_mul_f32_e32 v35, v39, v80
	v_cvt_pk_bf16_f32 v195, v32, v33
	v_cvt_pk_bf16_f32 v194, v34, v35
	v_mul_f32_e32 v32, v40, v80
	v_mul_f32_e32 v33, v41, v80
	v_mul_f32_e32 v34, v42, v80
	v_mul_f32_e32 v35, v43, v80
	v_mul_f32_e32 v16, v16, v80
	v_mul_f32_e32 v17, v17, v80
	v_cvt_pk_bf16_f32 v189, v32, v33
	v_cvt_pk_bf16_f32 v188, v34, v35
	v_mul_f32_e32 v32, v44, v80
	v_mul_f32_e32 v33, v45, v80
	v_mul_f32_e32 v34, v46, v80
	v_mul_f32_e32 v35, v47, v80
	v_cvt_pk_bf16_f32 v191, v32, v33
	v_cvt_pk_bf16_f32 v190, v34, v35
	v_cvt_pk_bf16_f32 v186, v16, v17
	v_mul_f32_e32 v16, v20, v80
	v_mul_f32_e32 v17, v21, v80
	v_mul_f32_e32 v18, v18, v80
	v_mul_f32_e32 v19, v19, v80
	v_cvt_pk_bf16_f32 v185, v18, v19
	v_cvt_pk_bf16_f32 v187, v16, v17
	v_mul_f32_e32 v16, v24, v80
	v_mul_f32_e32 v17, v25, v80
	v_mul_f32_e32 v18, v22, v80
	v_mul_f32_e32 v19, v23, v80
	v_cvt_pk_bf16_f32 v184, v18, v19
	v_cvt_pk_bf16_f32 v165, v16, v17
	v_mul_f32_e32 v16, v28, v80
	v_mul_f32_e32 v17, v29, v80
	s_mul_i32 s4, s26, 0x220000
	s_lshl_b32 s26, s26, 7
	s_mov_b32 s27, s5
	v_mul_f32_e32 v18, v26, v80
	v_mul_f32_e32 v19, v27, v80
	v_cvt_pk_bf16_f32 v164, v18, v19
	v_cvt_pk_bf16_f32 v167, v16, v17
	v_lshl_add_u64 v[16:17], v[150:151], 0, s[26:27]
	v_mov_b32_e32 v135, v131
	v_lshl_add_u64 v[16:17], v[16:17], 0, v[134:135]
	v_mul_f32_e32 v18, v30, v80
	v_mul_f32_e32 v19, v31, v80
	v_cvt_pk_bf16_f32 v166, v18, v19
	global_load_dwordx4 v[112:115], v[16:17], off
	global_load_dwordx4 v[116:119], v[16:17], off offset:32
	global_load_dwordx4 v[120:123], v[16:17], off offset:64
	global_load_dwordx4 v[124:127], v[16:17], off offset:96
	v_lshl_add_u64 v[16:17], v[140:141], 0, s[4:5]
	v_readfirstlane_b32 s4, v182
	v_lshl_add_u64 v[18:19], v[16:17], 0, s[16:17]
	s_mov_b32 m0, s4
	v_readfirstlane_b32 s4, v209
	s_waitcnt vmcnt(0)
	s_barrier
	global_load_lds_dwordx4 v[18:19], off
	s_mov_b32 m0, s4
	v_readfirstlane_b32 s4, v211
	global_load_lds_dwordx4 v[152:153], off
	s_mov_b32 m0, s4
	v_readfirstlane_b32 s4, v213
	global_load_lds_dwordx4 v[154:155], off
	v_lshl_add_u64 v[18:19], v[16:17], 0, s[18:19]
	s_mov_b32 m0, s4
	v_readfirstlane_b32 s4, v215
	global_load_lds_dwordx4 v[18:19], off
	s_mov_b32 m0, s4
	v_readfirstlane_b32 s4, v217
	global_load_lds_dwordx4 v[156:157], off
	s_mov_b32 m0, s4
	v_readfirstlane_b32 s4, v218
	global_load_lds_dwordx4 v[158:159], off
	v_lshl_add_u64 v[16:17], v[16:17], 0, s[22:23]
	s_mov_b32 m0, s4
	v_readfirstlane_b32 s4, v219
	global_load_lds_dwordx4 v[16:17], off
	s_mov_b32 m0, s4
	v_readfirstlane_b32 s4, v220
	global_load_lds_dwordx4 v[160:161], off
	s_mov_b32 m0, s4
	v_mov_b32_e32 v135, 0
	global_load_lds_dwordx4 v[162:163], off
	s_waitcnt vmcnt(6)
	v_lshl_add_u64 v[150:151], v[146:147], 0, s[24:25]
	s_mov_b32 s4, 0
	s_mov_b32 s22, 0x18000
	v_mov_b32_e32 v64, 0
	v_mov_b32_e32 v65, v135
	v_mov_b32_e32 v66, v135
	v_mov_b32_e32 v67, v135
	v_mov_b32_e32 v68, v135
	v_mov_b32_e32 v69, v135
	v_mov_b32_e32 v70, v135
	v_mov_b32_e32 v71, v135
	v_mov_b32_e32 v72, v135
	v_mov_b32_e32 v73, v135
	v_mov_b32_e32 v74, v135
	v_mov_b32_e32 v75, v135
	v_mov_b32_e32 v76, v135
	v_mov_b32_e32 v77, v135
	v_mov_b32_e32 v78, v135
	v_mov_b32_e32 v79, v135
	v_mov_b32_e32 v48, 0
	v_mov_b32_e32 v49, v135
	v_mov_b32_e32 v50, v135
	v_mov_b32_e32 v51, v135
	v_mov_b32_e32 v52, v135
	v_mov_b32_e32 v53, v135
	v_mov_b32_e32 v54, v135
	v_mov_b32_e32 v55, v135
	v_mov_b32_e32 v56, v135
	v_mov_b32_e32 v57, v135
	v_mov_b32_e32 v58, v135
	v_mov_b32_e32 v59, v135
	v_mov_b32_e32 v60, v135
	v_mov_b32_e32 v61, v135
	v_mov_b32_e32 v62, v135
	v_mov_b32_e32 v63, v135
	v_mov_b32_e32 v32, 0
	v_mov_b32_e32 v33, v135
	v_mov_b32_e32 v34, v135
	v_mov_b32_e32 v35, v135
	v_mov_b32_e32 v36, v135
	v_mov_b32_e32 v37, v135
	v_mov_b32_e32 v38, v135
	v_mov_b32_e32 v39, v135
	v_mov_b32_e32 v40, v135
	v_mov_b32_e32 v41, v135
	v_mov_b32_e32 v42, v135
	v_mov_b32_e32 v43, v135
	v_mov_b32_e32 v44, v135
	v_mov_b32_e32 v45, v135
	v_mov_b32_e32 v46, v135
	v_mov_b32_e32 v47, v135
	v_mov_b32_e32 v16, 0
	v_mov_b32_e32 v17, v135
	v_mov_b32_e32 v18, v135
	v_mov_b32_e32 v19, v135
	v_mov_b32_e32 v20, v135
	v_mov_b32_e32 v21, v135
	v_mov_b32_e32 v22, v135
	v_mov_b32_e32 v23, v135
	v_mov_b32_e32 v24, v135
	v_mov_b32_e32 v25, v135
	v_mov_b32_e32 v26, v135
	v_mov_b32_e32 v27, v135
	v_mov_b32_e32 v28, v135
	v_mov_b32_e32 v29, v135
	v_mov_b32_e32 v30, v135
	v_mov_b32_e32 v31, v135
	s_barrier
	s_mov_b32 s90, 0
	s_mov_b32 s88, 0
	s_mov_b32 s89, 0
	s_lshr_b32 s91, s2, 7
	s_lshl_b32 s92, s98, 1
	s_add_i32 s91, s91, s92
	s_mul_i32 s92, s91, 0xab
	s_lshr_b32 s92, s92, 9
	s_mul_i32 s93, s92, 3
	s_sub_i32 s91, s91, s93
	v_mbcnt_lo_u32_b32 v222, -1, 0
	v_mbcnt_hi_u32_b32 v222, -1, v222
	s_and_b32 s93, s2, 0x7f
	s_lshl_b32 s93, s93, 9
	s_or_b32 s93, s93, s63
	v_or_b32_e32 v222, s93, v222
	s_cmp_eq_u32 s91, 2
	s_cselect_b32 s93, 12, 11
	v_lshrrev_b32_e32 v223, s93, v222
	v_and_b32_e32 v208, 7, v222
	v_lshl_or_b32 v223, v223, 3, v208
	s_cselect_b32 s93, 6, 5
	v_bfe_u32 v208, v222, 6, s93
	v_lshrrev_b32_e32 v222, 1, v222
	v_and_b32_e32 v222, 28, v222
	v_lshl_or_b32 v222, v208, 5, v222
	v_lshlrev_b32_e32 v222, 2, v222
	s_cselect_b32 s93, 16, 15
	v_lshlrev_b32_e32 v223, s93, v223
	v_add_u32_e32 v222, v223, v222
	s_cselect_b32 s94, 1, 0
	s_lshl_b32 s94, 0x1000, s94
	s_lshl_b32 s92, s92, 23
	s_cmp_eq_u32 s91, 0
	s_cselect_b64 s[100:101], s[76:77], s[78:79]
	s_cmp_eq_u32 s91, 2
	s_cselect_b64 s[100:101], s[80:81], s[100:101]
	s_add_u32 s100, s100, s92
	s_addc_u32 s101, s101, 0
	s_mov_b32 s95, 1
	s_cmp_eq_u32 s97, 0
	s_cselect_b32 s95, 0, s95
	s_branch .LBB0_1457
